# FoX: second unit of each workgroup taken from the partner head (heads paired by forget-bias rank) for load balance; K pass every unit
# speedup vs baseline: 1.0147x; 1.0057x over previous
.LBB0_558:
	ds_bpermute_b32 v32, v151, v163
	s_mov_b32 s35, s81
	v_cndmask_b32_e64 v190, 16, 0, s[40:41]
	s_brev_b32 s2, 32
	s_mov_b64 s[36:37], 0
	s_waitcnt lgkmcnt(0)
	v_add_f32_e32 v32, v163, v32
	v_div_scale_f32 v33, s[20:21], v32, v32, 1.0
	v_rcp_f32_e32 v34, v33
	s_mov_b64 s[20:21], 0x4000400
	v_fma_f32 v35, -v33, v34, 1.0
	v_fmac_f32_e32 v34, v35, v34
	v_div_scale_f32 v35, vcc, 1.0, v32, 1.0
	v_mul_f32_e32 v36, v35, v34
	v_fma_f32 v37, -v33, v36, v35
	v_fmac_f32_e32 v36, v37, v34
	v_fma_f32 v33, -v33, v36, v35
	v_div_fmas_f32 v33, v33, v34, v36
	v_div_fixup_f32 v32, v33, v32, 1.0
	v_pk_mul_f32 v[10:11], v[10:11], v[32:33] op_sel_hi:[1,0]
	s_waitcnt vmcnt(1)
	v_lshlrev_b32_e32 v34, 16, v143
	v_and_b32_e32 v35, 0xffff0000, v143
	v_pk_mul_f32 v[10:11], v[10:11], v[34:35]
	v_pk_mul_f32 v[8:9], v[8:9], v[32:33] op_sel_hi:[1,0]
	v_lshlrev_b32_e32 v34, 16, v142
	v_and_b32_e32 v35, 0xffff0000, v142
	v_pk_mul_f32 v[8:9], v[8:9], v[34:35]
	v_cvt_pk_bf16_f32 v11, v10, v11
	v_cvt_pk_bf16_f32 v10, v8, v9
	v_pk_mul_f32 v[6:7], v[6:7], v[32:33] op_sel_hi:[1,0]
	v_lshlrev_b32_e32 v8, 16, v141
	v_and_b32_e32 v9, 0xffff0000, v141
	v_pk_mul_f32 v[6:7], v[6:7], v[8:9]
	v_pk_mul_f32 v[4:5], v[4:5], v[32:33] op_sel_hi:[1,0]
	v_lshlrev_b32_e32 v8, 16, v140
	v_and_b32_e32 v9, 0xffff0000, v140
	v_pk_mul_f32 v[4:5], v[4:5], v[8:9]
	v_cvt_pk_bf16_f32 v7, v6, v7
	v_cvt_pk_bf16_f32 v6, v4, v5
	v_pk_mul_f32 v[2:3], v[2:3], v[32:33] op_sel_hi:[1,0]
	v_lshlrev_b32_e32 v4, 16, v139
	v_and_b32_e32 v5, 0xffff0000, v139
	v_pk_mul_f32 v[2:3], v[2:3], v[4:5]
	v_pk_mul_f32 v[0:1], v[0:1], v[32:33] op_sel_hi:[1,0]
	v_cvt_pk_bf16_f32 v5, v2, v3
	v_lshlrev_b32_e32 v2, 16, v138
	v_and_b32_e32 v3, 0xffff0000, v138
	v_pk_mul_f32 v[0:1], v[0:1], v[2:3]
	v_lshlrev_b32_e32 v2, 16, v137
	v_cvt_pk_bf16_f32 v4, v0, v1
	v_pk_mul_f32 v[0:1], v[30:31], v[32:33] op_sel_hi:[1,0]
	v_and_b32_e32 v3, 0xffff0000, v137
	v_pk_mul_f32 v[0:1], v[0:1], v[2:3]
	v_lshlrev_b32_e32 v8, 16, v136
	v_cvt_pk_bf16_f32 v3, v0, v1
	v_pk_mul_f32 v[0:1], v[28:29], v[32:33] op_sel_hi:[1,0]
	v_and_b32_e32 v9, 0xffff0000, v136
	v_pk_mul_f32 v[0:1], v[0:1], v[8:9]
	v_lshlrev_b32_e32 v8, 16, v135
	v_cvt_pk_bf16_f32 v2, v0, v1
	v_pk_mul_f32 v[0:1], v[26:27], v[32:33] op_sel_hi:[1,0]
	v_and_b32_e32 v9, 0xffff0000, v135
	v_pk_mul_f32 v[0:1], v[0:1], v[8:9]
	v_pk_mul_f32 v[8:9], v[24:25], v[32:33] op_sel_hi:[1,0]
	v_lshlrev_b32_e32 v24, 16, v134
	v_and_b32_e32 v25, 0xffff0000, v134
	v_pk_mul_f32 v[8:9], v[8:9], v[24:25]
	v_cvt_pk_bf16_f32 v1, v0, v1
	v_cvt_pk_bf16_f32 v0, v8, v9
	v_pk_mul_f32 v[8:9], v[22:23], v[32:33] op_sel_hi:[1,0]
	v_lshlrev_b32_e32 v22, 16, v133
	v_and_b32_e32 v23, 0xffff0000, v133
	v_pk_mul_f32 v[8:9], v[8:9], v[22:23]
	v_pk_mul_f32 v[12:13], v[12:13], v[32:33] op_sel_hi:[1,0]
	v_cvt_pk_bf16_f32 v23, v8, v9
	v_pk_mul_f32 v[8:9], v[20:21], v[32:33] op_sel_hi:[1,0]
	v_lshlrev_b32_e32 v20, 16, v132
	v_and_b32_e32 v21, 0xffff0000, v132
	v_pk_mul_f32 v[8:9], v[8:9], v[20:21]
	v_pk_mul_f32 v[14:15], v[14:15], v[32:33] op_sel_hi:[1,0]
	v_cvt_pk_bf16_f32 v22, v8, v9
	v_pk_mul_f32 v[8:9], v[18:19], v[32:33] op_sel_hi:[1,0]
	v_lshlrev_b32_e32 v18, 16, v131
	v_and_b32_e32 v19, 0xffff0000, v131
	v_pk_mul_f32 v[8:9], v[8:9], v[18:19]
	v_permlane32_swap_b32_e32 v0, v2
	v_cvt_pk_bf16_f32 v21, v8, v9
	v_pk_mul_f32 v[8:9], v[16:17], v[32:33] op_sel_hi:[1,0]
	v_lshlrev_b32_e32 v16, 16, v130
	v_and_b32_e32 v17, 0xffff0000, v130
	v_pk_mul_f32 v[8:9], v[8:9], v[16:17]
	s_waitcnt vmcnt(0)
	v_lshlrev_b32_e32 v16, 16, v128
	v_cvt_pk_bf16_f32 v20, v8, v9
	v_lshlrev_b64 v[8:9], 11, v[144:145]
	v_lshl_add_u64 v[8:9], s[18:19], 0, v[8:9]
	v_and_b32_e32 v17, 0xffff0000, v128
	v_pk_mul_f32 v[12:13], v[12:13], v[16:17]
	v_lshlrev_b32_e32 v16, 16, v129
	v_and_b32_e32 v17, 0xffff0000, v129
	v_lshl_add_u64 v[8:9], v[8:9], 0, s[34:35]
	v_pk_mul_f32 v[14:15], v[14:15], v[16:17]
	v_lshl_add_u64 v[8:9], v[8:9], 0, v[190:191]
	v_cvt_pk_bf16_f32 v12, v12, v13
	v_cvt_pk_bf16_f32 v13, v14, v15
	v_lshl_add_u64 v[14:15], v[8:9], 0, s[20:21]
	v_add_co_u32_e32 v8, vcc, s2, v8
	v_permlane32_swap_b32_e32 v20, v22
	s_nop 0
	v_addc_co_u32_e32 v9, vcc, 0, v9, vcc
	v_permlane32_swap_b32_e32 v21, v23
	v_permlane32_swap_b32_e32 v1, v3
	v_permlane32_swap_b32_e32 v4, v6
	v_permlane32_swap_b32_e32 v5, v7
	v_permlane32_swap_b32_e32 v10, v12
	v_permlane32_swap_b32_e32 v11, v13
	s_and_b64 vcc, exec, s[44:45]
	global_store_dwordx4 v[8:9], v[20:23], off offset:1024
	global_store_dwordx4 v[14:15], v[0:3], off offset:32
	global_store_dwordx4 v[14:15], v[4:7], off offset:64
	global_store_dwordx4 v[14:15], v[10:13], off offset:96
	s_cbranch_vccnz .LBB0_556
	s_ashr_i32 s100, s14, 3
	s_ashr_i32 s101, s14, 6
	s_load_dwordx2 s[2:3], s[0:1], 0x50
	s_waitcnt lgkmcnt(0)
	s_lshl_b32 s20, s16, 5
	s_add_u32 s2, s2, s20
	s_addc_u32 s3, s3, 0
	v_and_b32_e32 v36, 7, v227
	v_lshlrev_b32_e32 v32, 2, v36
	global_load_dword v33, v32, s[2:3]
	s_waitcnt vmcnt(0)
	v_ashrrev_i32_e32 v35, 31, v33
	v_and_b32_e32 v35, 0x7fffffff, v35
	v_xor_b32_e32 v33, v33, v35
	v_mov_b32_e32 v34, 0
	s_nop 1
	v_readlane_b32 s2, v33, 0
	s_nop 3
	v_cmp_lt_i32_e64 s[20:21], s2, v33
	v_cmp_eq_i32_e64 s[42:43], s2, v33
	v_cmp_gt_u32_e64 vcc, v36, 0
	s_nop 3
	s_and_b64 s[42:43], s[42:43], vcc
	s_or_b64 s[20:21], s[20:21], s[42:43]
	s_nop 3
	v_cndmask_b32_e64 v35, 0, 1, s[20:21]
	v_add_u32_e32 v34, v34, v35
	v_readlane_b32 s2, v33, 1
	s_nop 3
	v_cmp_lt_i32_e64 s[20:21], s2, v33
	v_cmp_eq_i32_e64 s[42:43], s2, v33
	v_cmp_gt_u32_e64 vcc, v36, 1
	s_nop 3
	s_and_b64 s[42:43], s[42:43], vcc
	s_or_b64 s[20:21], s[20:21], s[42:43]
	s_nop 3
	v_cndmask_b32_e64 v35, 0, 1, s[20:21]
	v_add_u32_e32 v34, v34, v35
	v_readlane_b32 s2, v33, 2
	s_nop 3
	v_cmp_lt_i32_e64 s[20:21], s2, v33
	v_cmp_eq_i32_e64 s[42:43], s2, v33
	v_cmp_gt_u32_e64 vcc, v36, 2
	s_nop 3
	s_and_b64 s[42:43], s[42:43], vcc
	s_or_b64 s[20:21], s[20:21], s[42:43]
	s_nop 3
	v_cndmask_b32_e64 v35, 0, 1, s[20:21]
	v_add_u32_e32 v34, v34, v35
	v_readlane_b32 s2, v33, 3
	s_nop 3
	v_cmp_lt_i32_e64 s[20:21], s2, v33
	v_cmp_eq_i32_e64 s[42:43], s2, v33
	v_cmp_gt_u32_e64 vcc, v36, 3
	s_nop 3
	s_and_b64 s[42:43], s[42:43], vcc
	s_or_b64 s[20:21], s[20:21], s[42:43]
	s_nop 3
	v_cndmask_b32_e64 v35, 0, 1, s[20:21]
	v_add_u32_e32 v34, v34, v35
	v_readlane_b32 s2, v33, 4
	s_nop 3
	v_cmp_lt_i32_e64 s[20:21], s2, v33
	v_cmp_eq_i32_e64 s[42:43], s2, v33
	v_cmp_gt_u32_e64 vcc, v36, 4
	s_nop 3
	s_and_b64 s[42:43], s[42:43], vcc
	s_or_b64 s[20:21], s[20:21], s[42:43]
	s_nop 3
	v_cndmask_b32_e64 v35, 0, 1, s[20:21]
	v_add_u32_e32 v34, v34, v35
	v_readlane_b32 s2, v33, 5
	s_nop 3
	v_cmp_lt_i32_e64 s[20:21], s2, v33
	v_cmp_eq_i32_e64 s[42:43], s2, v33
	v_cmp_gt_u32_e64 vcc, v36, 5
	s_nop 3
	s_and_b64 s[42:43], s[42:43], vcc
	s_or_b64 s[20:21], s[20:21], s[42:43]
	s_nop 3
	v_cndmask_b32_e64 v35, 0, 1, s[20:21]
	v_add_u32_e32 v34, v34, v35
	v_readlane_b32 s2, v33, 6
	s_nop 3
	v_cmp_lt_i32_e64 s[20:21], s2, v33
	v_cmp_eq_i32_e64 s[42:43], s2, v33
	v_cmp_gt_u32_e64 vcc, v36, 6
	s_nop 3
	s_and_b64 s[42:43], s[42:43], vcc
	s_or_b64 s[20:21], s[20:21], s[42:43]
	s_nop 3
	v_cndmask_b32_e64 v35, 0, 1, s[20:21]
	v_add_u32_e32 v34, v34, v35
	v_readlane_b32 s2, v33, 7
	s_nop 3
	v_cmp_lt_i32_e64 s[20:21], s2, v33
	v_cmp_eq_i32_e64 s[42:43], s2, v33
	v_cmp_gt_u32_e64 vcc, v36, 7
	s_nop 3
	s_and_b64 s[42:43], s[42:43], vcc
	s_or_b64 s[20:21], s[20:21], s[42:43]
	s_nop 3
	v_cndmask_b32_e64 v35, 0, 1, s[20:21]
	v_add_u32_e32 v34, v34, v35
	s_and_b32 s3, s100, 7
	s_nop 3
	v_readlane_b32 s2, v34, s3
	s_nop 3
	s_sub_i32 s2, 7, s2
	v_cmp_eq_u32_e64 s[20:21], s2, v34
	s_nop 3
	s_and_b32 s20, s20, 0xff
	s_ff1_i32_b32 s2, s20
	s_and_b32 s2, s2, 7
	s_andn2_b32 s100, s100, 7
	s_or_b32 s100, s100, s2
	s_lshl_b32 s2, s100, 14
	s_add_u32 s26, s10, s2
	s_addc_u32 s27, s11, 0
	s_lshl_b32 s2, s100, 6
	s_lshl_b32 s20, s100, 7
	s_mul_i32 s21, s101, 0x1e00000
	s_and_b32 s20, s20, 0x380
	s_and_b32 s2, s2, 0x1c0
	s_or_b32 s20, s21, s20
	s_mul_hi_i32 s3, s101, 0x1e00000
	s_add_u32 s28, s18, s20
	s_addc_u32 s29, s19, s3
	s_add_u32 s30, s12, s20
	s_addc_u32 s31, s13, s3
	s_lshl_b32 s34, s2, 1

.LBB0_574:
	v_readfirstlane_b32 s2, v165
	s_nop 3
	s_lshr_b32 s2, s2, 6
	s_lshl_b32 s2, s2, 5
	s_lshl_b32 s3, s48, 8
	s_add_i32 s2, s2, s3
	s_add_i32 s20, s2, -32
	s_lshl_b32 s42, s20, 2
	s_mul_i32 s20, s20, 0x1e00
	s_add_u32 s20, s20, 0x7001200
	s_add_u32 s2, s28, s20
	s_addc_u32 s3, s29, 0
	v_and_b32_e32 v60, 31, v165
	v_mul_u32_u24_e32 v60, 0x1e00, v60
	v_bfe_u32 v61, v165, 5, 1
	v_lshl_add_u32 v60, v61, 4, v60
	v_add_u32_e32 v61, s42, v179
	global_load_dwordx4 v[64:67], v60, s[2:3] offset:0
	global_load_dwordx4 v[68:71], v60, s[2:3] offset:32
	global_load_dwordx4 v[72:75], v60, s[2:3] offset:64
	global_load_dwordx4 v[76:79], v60, s[2:3] offset:96
	ds_read_b128 v[32:35], v61
	ds_read_b128 v[36:39], v61 offset:32
	ds_read_b128 v[40:43], v61 offset:64
	ds_read_b128 v[44:47], v61 offset:96
	s_waitcnt lgkmcnt(0)
	s_waitcnt vmcnt(3)
	v_mfma_f32_32x32x16_bf16 v[32:47], v[64:67], v[96:99], v[32:47]
	s_waitcnt vmcnt(2)
	v_mfma_f32_32x32x16_bf16 v[32:47], v[68:71], v[100:103], v[32:47]
	s_waitcnt vmcnt(1)
	v_mfma_f32_32x32x16_bf16 v[32:47], v[72:75], v[104:107], v[32:47]
	s_waitcnt vmcnt(0)
	v_mfma_f32_32x32x16_bf16 v[32:47], v[76:79], v[108:111], v[32:47]
	s_nop 11
	v_max3_f32 v222, v32, v33, v34
	v_max3_f32 v222, v222, v35, v36
	v_max3_f32 v222, v222, v37, v38
	v_max3_f32 v222, v222, v39, v40
	v_max3_f32 v222, v222, v41, v42
	v_max3_f32 v222, v222, v43, v44
	v_max3_f32 v222, v222, v45, v46
	v_max_f32_e32 v222, v222, v47
	ds_bpermute_b32 v183, v180, v222
	s_waitcnt lgkmcnt(0)
	v_max_f32_e32 v183, v183, v183
	v_max_f32_e32 v182, v222, v183
	v_sub_f32_e32 v182, v182, v161
	v_add_f32_e32 v255, 0xc2200000, v182
	s_mov_b64 s[2:3], 0x7001200
	v_lshl_add_u64 v[202:203], v[158:159], 0, s[2:3]
	s_mov_b64 s[2:3], 0x78000
	v_lshl_add_u64 v[204:205], v[202:203], 0, s[2:3]
	v_mov_b32_e32 v210, 0
	s_lshl_b32 s20, s48, 1
	s_add_i32 s100, s20, 1
	s_add_i32 s20, s48, 1
	s_lshr_b32 s20, s20, 1
	s_mov_b32 s101, 0
	s_mov_b32 s3, 0
	s_min_u32 s2, s101, s100
	s_mul_i32 s2, s2, 0xf0000
	s_add_i32 s101, s101, 1
	v_lshl_add_u64 v[206:207], v[202:203], 0, s[2:3]
	v_lshl_add_u64 v[208:209], v[204:205], 0, s[2:3]
	global_load_dwordx4 v[32:35], v[206:207], off
	global_load_dwordx4 v[36:39], v[208:209], off
	s_min_u32 s2, s101, s100
	s_mul_i32 s2, s2, 0xf0000
	s_add_i32 s101, s101, 1
	v_lshl_add_u64 v[206:207], v[202:203], 0, s[2:3]
	v_lshl_add_u64 v[208:209], v[204:205], 0, s[2:3]
	global_load_dwordx4 v[40:43], v[206:207], off
	global_load_dwordx4 v[44:47], v[208:209], off
	s_min_u32 s2, s101, s100
	s_mul_i32 s2, s2, 0xf0000
	s_add_i32 s101, s101, 1
	v_lshl_add_u64 v[206:207], v[202:203], 0, s[2:3]
	v_lshl_add_u64 v[208:209], v[204:205], 0, s[2:3]
	global_load_dwordx4 v[48:51], v[206:207], off
	global_load_dwordx4 v[52:55], v[208:209], off
	s_min_u32 s2, s101, s100
	s_mul_i32 s2, s2, 0xf0000
	s_add_i32 s101, s101, 1
	v_lshl_add_u64 v[206:207], v[202:203], 0, s[2:3]
	v_lshl_add_u64 v[208:209], v[204:205], 0, s[2:3]
	global_load_dwordx4 v[56:59], v[206:207], off
	global_load_dwordx4 v[60:63], v[208:209], off
	s_min_u32 s2, s101, s100
	s_mul_i32 s2, s2, 0xf0000
	s_add_i32 s101, s101, 1
	v_lshl_add_u64 v[206:207], v[202:203], 0, s[2:3]
	v_lshl_add_u64 v[208:209], v[204:205], 0, s[2:3]
	global_load_dwordx4 v[64:67], v[206:207], off
	global_load_dwordx4 v[68:71], v[208:209], off
	s_min_u32 s2, s101, s100
	s_mul_i32 s2, s2, 0xf0000
	s_add_i32 s101, s101, 1
	v_lshl_add_u64 v[206:207], v[202:203], 0, s[2:3]
	v_lshl_add_u64 v[208:209], v[204:205], 0, s[2:3]
	global_load_dwordx4 v[72:75], v[206:207], off
	global_load_dwordx4 v[76:79], v[208:209], off
	s_min_u32 s2, s101, s100
	s_mul_i32 s2, s2, 0xf0000
	s_add_i32 s101, s101, 1
	v_lshl_add_u64 v[206:207], v[202:203], 0, s[2:3]
	v_lshl_add_u64 v[208:209], v[204:205], 0, s[2:3]
	global_load_dwordx4 v[80:83], v[206:207], off
	global_load_dwordx4 v[84:87], v[208:209], off
	s_min_u32 s2, s101, s100
	s_mul_i32 s2, s2, 0xf0000
	s_add_i32 s101, s101, 1
	v_lshl_add_u64 v[206:207], v[202:203], 0, s[2:3]
	v_lshl_add_u64 v[208:209], v[204:205], 0, s[2:3]
	global_load_dwordx4 v[88:91], v[206:207], off
	global_load_dwordx4 v[92:95], v[208:209], off
